# grid barrier: non-leader workgroups poll the top-level generation word directly (one relay hop less per barrier)
# speedup vs baseline: 1.0057x; 1.0057x over previous
.LBB0_91:
	s_or_b64 exec, exec, s[12:13]
	v_cvt_f32_u32_e32 v4, v2
	s_waitcnt vmcnt(0)
	v_readfirstlane_b32 s10, v3
	v_sub_u32_e32 v3, 0, v2
	v_rcp_iflag_f32_e32 v4, v4
	v_add_u32_e32 v5, s10, v1
	v_mul_f32_e32 v4, 0x4f7ffffe, v4
	v_cvt_u32_f32_e32 v4, v4
	v_mul_lo_u32 v1, v3, v4
	v_mul_hi_u32 v1, v4, v1
	v_add_u32_e32 v1, v4, v1
	v_mul_hi_u32 v1, v5, v1
	v_mul_lo_u32 v3, v1, v2
	v_sub_u32_e32 v3, v5, v3
	v_add_u32_e32 v4, 1, v1
	v_cmp_ge_u32_e32 vcc, v3, v2
	s_nop 1
	v_cndmask_b32_e32 v1, v1, v4, vcc
	v_sub_u32_e32 v4, v3, v2
	v_cndmask_b32_e32 v3, v3, v4, vcc
	v_add_u32_e32 v4, 1, v1
	v_cmp_ge_u32_e32 vcc, v3, v2
	v_add_u32_e32 v3, 1, v5
	s_nop 0
	v_cndmask_b32_e32 v1, v1, v4, vcc
	v_mul_lo_u32 v4, v2, v1
	v_add_u32_e32 v2, v4, v2
	v_cmp_ne_u32_e32 vcc, v3, v2
	s_and_saveexec_b64 s[10:11], vcc
	s_xor_b64 s[10:11], exec, s[10:11]
	s_cbranch_execz .LBB0_105
	s_waitcnt lgkmcnt(0)
	s_add_u32 s18, s34, 0xed10500
	s_addc_u32 s19, s35, 0
	v_mov_b32_e32 v0, 0
	global_load_dword v0, v0, s[18:19] sc1
	s_waitcnt vmcnt(0)
	v_cmp_eq_u32_e32 vcc, v0, v1
	s_and_saveexec_b64 s[12:13], vcc
	s_cbranch_execz .LBB0_104
	s_add_u32 s16, s34, 0xed0d200
	s_addc_u32 s17, s35, 0
	s_mov_b32 s14, 1
	s_mov_b64 s[20:21], 0
	v_mov_b32_e32 v0, 0
	s_branch .LBB0_95

.LBB0_1289:
	s_or_b64 exec, exec, s[10:11]
	v_cvt_f32_u32_e32 v4, v2
	s_waitcnt vmcnt(0)
	v_readfirstlane_b32 s8, v3
	v_sub_u32_e32 v3, 0, v2
	v_rcp_iflag_f32_e32 v4, v4
	v_add_u32_e32 v5, s8, v1
	v_mul_f32_e32 v4, 0x4f7ffffe, v4
	v_cvt_u32_f32_e32 v4, v4
	v_mul_lo_u32 v1, v3, v4
	v_mul_hi_u32 v1, v4, v1
	v_add_u32_e32 v1, v4, v1
	v_mul_hi_u32 v1, v5, v1
	v_mul_lo_u32 v3, v1, v2
	v_sub_u32_e32 v3, v5, v3
	v_add_u32_e32 v4, 1, v1
	v_cmp_ge_u32_e32 vcc, v3, v2
	s_nop 1
	v_cndmask_b32_e32 v1, v1, v4, vcc
	v_sub_u32_e32 v4, v3, v2
	v_cndmask_b32_e32 v3, v3, v4, vcc
	v_add_u32_e32 v4, 1, v1
	v_cmp_ge_u32_e32 vcc, v3, v2
	v_add_u32_e32 v3, 1, v5
	s_nop 0
	v_cndmask_b32_e32 v1, v1, v4, vcc
	v_mul_lo_u32 v4, v2, v1
	v_add_u32_e32 v2, v4, v2
	v_cmp_ne_u32_e32 vcc, v3, v2
	s_and_saveexec_b64 s[8:9], vcc
	s_xor_b64 s[8:9], exec, s[8:9]
	s_cbranch_execz .LBB0_1303
	s_waitcnt lgkmcnt(0)
	s_add_u32 s16, s34, 0xed10500
	s_addc_u32 s17, s35, 0
	v_mov_b32_e32 v0, 0
	global_load_dword v0, v0, s[16:17] sc1
	s_waitcnt vmcnt(0)
	v_cmp_eq_u32_e32 vcc, v0, v1
	s_and_saveexec_b64 s[10:11], vcc
	s_cbranch_execz .LBB0_1302
	s_add_u32 s12, s34, 0xed0d200
	s_addc_u32 s13, s35, 0
	s_mov_b32 s14, 1
	s_mov_b64 s[18:19], 0
	v_mov_b32_e32 v0, 0
	s_branch .LBB0_1293

.LBB0_1533:
	s_or_b64 exec, exec, s[12:13]
	v_cvt_f32_u32_e32 v4, v2
	s_waitcnt vmcnt(0)
	v_readfirstlane_b32 s3, v3
	v_sub_u32_e32 v3, 0, v2
	v_rcp_iflag_f32_e32 v4, v4
	v_add_u32_e32 v5, s3, v1
	v_mul_f32_e32 v4, 0x4f7ffffe, v4
	v_cvt_u32_f32_e32 v4, v4
	v_mul_lo_u32 v1, v3, v4
	v_mul_hi_u32 v1, v4, v1
	v_add_u32_e32 v1, v4, v1
	v_mul_hi_u32 v1, v5, v1
	v_mul_lo_u32 v3, v1, v2
	v_sub_u32_e32 v3, v5, v3
	v_add_u32_e32 v4, 1, v1
	v_cmp_ge_u32_e32 vcc, v3, v2
	s_nop 1
	v_cndmask_b32_e32 v1, v1, v4, vcc
	v_sub_u32_e32 v4, v3, v2
	v_cndmask_b32_e32 v3, v3, v4, vcc
	v_add_u32_e32 v4, 1, v1
	v_cmp_ge_u32_e32 vcc, v3, v2
	v_add_u32_e32 v3, 1, v5
	s_nop 0
	v_cndmask_b32_e32 v1, v1, v4, vcc
	v_mul_lo_u32 v4, v2, v1
	v_add_u32_e32 v2, v4, v2
	v_cmp_ne_u32_e32 vcc, v3, v2
	s_and_saveexec_b64 s[10:11], vcc
	s_xor_b64 s[10:11], exec, s[10:11]
	s_cbranch_execz .LBB0_1547
	s_waitcnt lgkmcnt(0)
	s_add_u32 s16, s34, 0xed10500
	s_addc_u32 s17, s35, 0
	v_mov_b32_e32 v0, 0
	global_load_dword v0, v0, s[16:17] sc1
	s_waitcnt vmcnt(0)
	v_cmp_eq_u32_e32 vcc, v0, v1
	s_and_saveexec_b64 s[12:13], vcc
	s_cbranch_execz .LBB0_1546
	s_add_u32 s14, s34, 0xed0d200
	s_addc_u32 s15, s35, 0
	s_mov_b32 s3, 1
	s_mov_b64 s[18:19], 0
	v_mov_b32_e32 v0, 0
	s_branch .LBB0_1537
